# strategy 7: attention softmax row max/sum all-reduce over 16 key lanes via DPP (quad_perm, row_half_mirror, row_mirror) instead of 31 serialized ds_bpermute round trips
# baseline (speedup 1.0000x reference)
; #define LAS __attribute__((address_space(3)))
; __device__ __forceinline__ void attn_phase(const Params& p, LAS unsigned char* lds) {
;     ...
;         f32x4 sa[16];
; #pragma unroll
;         for (int kb = 0; kb < 16; ++kb) {
;             sa[kb] = (f32x4){0.f, 0.f, 0.f, 0.f};
; #pragma unroll
;             for (int ks = 0; ks < 4; ++ks) {
;                 const bf16x8 Kf = *(const LAS bf16x8*)(KL + (kb * 16 + fr) * 136 + ks * 32 + fq * 8);
;                 sa[kb] = __builtin_amdgcn_mfma_f32_16x16x32_bf16(Qf[ks], Kf, sa[kb], 0, 0, 0);
;             }
;         }
.LBB0_210:
	s_or_b64 exec, exec, s[86:87]
	s_waitcnt lgkmcnt(0)
	s_barrier
	ds_read_b128 v[36:39], v139
	ds_read_b128 v[40:43], v139 offset:64
	s_waitcnt lgkmcnt(1)
	v_mfma_f32_16x16x32_bf16 v[36:39], v[96:99], v[36:39], 0
	s_cmp_lg_u32 s33, 0
	v_readlane_b32 s78, v239, 40
	s_cselect_b64 s[40:41], -1, 0
	s_waitcnt lgkmcnt(0)
	v_mfma_f32_16x16x32_bf16 v[36:39], v[92:95], v[40:43], v[36:39]
	ds_read_b128 v[40:43], v139 offset:128
	v_readlane_b32 s79, v239, 41
	s_and_b64 vcc, s[40:41], s[78:79]
	s_waitcnt lgkmcnt(0)
	v_mfma_f32_16x16x32_bf16 v[36:39], v[88:91], v[40:43], v[36:39]
	ds_read_b128 v[40:43], v139 offset:192
	v_readlane_b32 s78, v239, 44
	v_readlane_b32 s79, v239, 45
	s_waitcnt lgkmcnt(0)
	v_mfma_f32_16x16x32_bf16 v[104:107], v[32:35], v[40:43], v[36:39]
	ds_read_b128 v[40:43], v139 offset:4416
	s_nop 1
	ds_read_b128 v[36:39], v139 offset:4352
	s_mov_b32 s33, 0xff61b1e6
	s_waitcnt lgkmcnt(0)
	v_mfma_f32_16x16x32_bf16 v[36:39], v[96:99], v[36:39], 0
	s_ashr_i32 s77, s76, 31
	s_lshl_b64 s[76:77], s[76:77], 14
	s_lshl_b32 s2, s2, 1
	v_mfma_f32_16x16x32_bf16 v[36:39], v[92:95], v[40:43], v[36:39]
	ds_read_b128 v[40:43], v139 offset:4480
	ds_read_b128 v[144:147], v139 offset:60992
	s_waitcnt lgkmcnt(1)
	v_mfma_f32_16x16x32_bf16 v[36:39], v[88:91], v[40:43], v[36:39]
	ds_read_b128 v[40:43], v139 offset:4544
	s_waitcnt lgkmcnt(0)
	v_mfma_f32_16x16x32_bf16 v[100:103], v[32:35], v[40:43], v[36:39]
	ds_read_b128 v[40:43], v139 offset:8768
	s_nop 3
	ds_read_b128 v[36:39], v139 offset:8704
	s_waitcnt lgkmcnt(0)
	v_mfma_f32_16x16x32_bf16 v[36:39], v[96:99], v[36:39], 0
	v_mfma_f32_16x16x32_bf16 v[36:39], v[92:95], v[40:43], v[36:39]
	ds_read_b128 v[40:43], v139 offset:8832
	s_waitcnt lgkmcnt(0)
	v_mfma_f32_16x16x32_bf16 v[36:39], v[88:91], v[40:43], v[36:39]
	ds_read_b128 v[40:43], v139 offset:8896
	s_waitcnt lgkmcnt(0)
	v_mfma_f32_16x16x32_bf16 v[84:87], v[32:35], v[40:43], v[36:39]
	ds_read_b128 v[40:43], v139 offset:13120
	s_nop 3
	ds_read_b128 v[36:39], v139 offset:13056
	s_waitcnt lgkmcnt(0)
	v_mfma_f32_16x16x32_bf16 v[36:39], v[96:99], v[36:39], 0
	v_mul_f32_e32 v84, 0x3db504f3, v84
	v_mul_f32_e32 v85, 0x3db504f3, v85
	v_mul_f32_e32 v86, 0x3db504f3, v86
	v_mfma_f32_16x16x32_bf16 v[36:39], v[92:95], v[40:43], v[36:39]
	ds_read_b128 v[40:43], v139 offset:13184
	v_mul_f32_e32 v87, 0x3db504f3, v87
	s_waitcnt lgkmcnt(0)
	v_mfma_f32_16x16x32_bf16 v[36:39], v[88:91], v[40:43], v[36:39]
	ds_read_b128 v[40:43], v139 offset:13248
	s_waitcnt lgkmcnt(0)
	v_mfma_f32_16x16x32_bf16 v[80:83], v[32:35], v[40:43], v[36:39]
	ds_read_b128 v[40:43], v139 offset:17472
	s_nop 3
	ds_read_b128 v[36:39], v139 offset:17408
	s_waitcnt lgkmcnt(0)
	v_mfma_f32_16x16x32_bf16 v[36:39], v[96:99], v[36:39], 0
	v_mul_f32_e32 v80, 0x3db504f3, v80
	v_mul_f32_e32 v81, 0x3db504f3, v81
	v_mul_f32_e32 v82, 0x3db504f3, v82
	v_mfma_f32_16x16x32_bf16 v[36:39], v[92:95], v[40:43], v[36:39]
	ds_read_b128 v[40:43], v139 offset:17536
	v_mul_f32_e32 v83, 0x3db504f3, v83
	s_waitcnt lgkmcnt(0)
	v_mfma_f32_16x16x32_bf16 v[36:39], v[88:91], v[40:43], v[36:39]
	ds_read_b128 v[40:43], v139 offset:17600
	s_waitcnt lgkmcnt(0)
	v_mfma_f32_16x16x32_bf16 v[76:79], v[32:35], v[40:43], v[36:39]
	ds_read_b128 v[40:43], v139 offset:21824
	s_nop 3
	ds_read_b128 v[36:39], v139 offset:21760
	s_waitcnt lgkmcnt(0)
	v_mfma_f32_16x16x32_bf16 v[36:39], v[96:99], v[36:39], 0
	v_mul_f32_e32 v76, 0x3db504f3, v76
	v_mul_f32_e32 v77, 0x3db504f3, v77
	v_mul_f32_e32 v78, 0x3db504f3, v78
	v_mfma_f32_16x16x32_bf16 v[36:39], v[92:95], v[40:43], v[36:39]
	ds_read_b128 v[40:43], v139 offset:21888
	v_mul_f32_e32 v79, 0x3db504f3, v79
	s_waitcnt lgkmcnt(0)
	v_mfma_f32_16x16x32_bf16 v[36:39], v[88:91], v[40:43], v[36:39]
	ds_read_b128 v[40:43], v139 offset:21952
	s_waitcnt lgkmcnt(0)
	v_mfma_f32_16x16x32_bf16 v[72:75], v[32:35], v[40:43], v[36:39]
	ds_read_b128 v[40:43], v139 offset:26176
	s_nop 3
	ds_read_b128 v[36:39], v139 offset:26112
	s_waitcnt lgkmcnt(0)
	v_mfma_f32_16x16x32_bf16 v[36:39], v[96:99], v[36:39], 0
	v_mul_f32_e32 v72, 0x3db504f3, v72
	v_mul_f32_e32 v73, 0x3db504f3, v73
	v_mul_f32_e32 v74, 0x3db504f3, v74
	v_mfma_f32_16x16x32_bf16 v[36:39], v[92:95], v[40:43], v[36:39]
	ds_read_b128 v[40:43], v139 offset:26240
	v_mul_f32_e32 v75, 0x3db504f3, v75
	s_waitcnt lgkmcnt(0)
	v_mfma_f32_16x16x32_bf16 v[36:39], v[88:91], v[40:43], v[36:39]
	ds_read_b128 v[40:43], v139 offset:26304
	s_waitcnt lgkmcnt(0)
	v_mfma_f32_16x16x32_bf16 v[68:71], v[32:35], v[40:43], v[36:39]
	ds_read_b128 v[40:43], v139 offset:30528
	s_nop 3
	ds_read_b128 v[36:39], v139 offset:30464
	s_waitcnt lgkmcnt(0)
	v_mfma_f32_16x16x32_bf16 v[36:39], v[96:99], v[36:39], 0
	v_mul_f32_e32 v68, 0x3db504f3, v68
	v_mul_f32_e32 v69, 0x3db504f3, v69
	v_mul_f32_e32 v70, 0x3db504f3, v70
	v_mfma_f32_16x16x32_bf16 v[36:39], v[92:95], v[40:43], v[36:39]
	ds_read_b128 v[40:43], v139 offset:30592
	v_mul_f32_e32 v71, 0x3db504f3, v71
	s_waitcnt lgkmcnt(0)
	v_mfma_f32_16x16x32_bf16 v[36:39], v[88:91], v[40:43], v[36:39]
	ds_read_b128 v[40:43], v139 offset:30656
	s_waitcnt lgkmcnt(0)
	v_mfma_f32_16x16x32_bf16 v[64:67], v[32:35], v[40:43], v[36:39]
	ds_read_b128 v[40:43], v139 offset:34880
	s_nop 3
	ds_read_b128 v[36:39], v139 offset:34816
	s_waitcnt lgkmcnt(0)
	v_mfma_f32_16x16x32_bf16 v[36:39], v[96:99], v[36:39], 0
	v_mul_f32_e32 v64, 0x3db504f3, v64
	v_mul_f32_e32 v65, 0x3db504f3, v65
	v_mul_f32_e32 v66, 0x3db504f3, v66
	v_mfma_f32_16x16x32_bf16 v[36:39], v[92:95], v[40:43], v[36:39]
	ds_read_b128 v[40:43], v139 offset:34944
	v_mul_f32_e32 v67, 0x3db504f3, v67
	s_waitcnt lgkmcnt(0)
	v_mfma_f32_16x16x32_bf16 v[36:39], v[88:91], v[40:43], v[36:39]
	ds_read_b128 v[40:43], v139 offset:35008
	s_waitcnt lgkmcnt(0)
; #define LAS __attribute__((address_space(3)))
; __device__ __forceinline__ void attn_phase(const Params& p, LAS unsigned char* lds) {
;     ...
; #pragma unroll
;         for (int kb = 0; kb < 16; ++kb) {
;             sa[kb] = (f32x4){0.f, 0.f, 0.f, 0.f};
; #pragma unroll
;             for (int ks = 0; ks < 4; ++ks) {
;                 const bf16x8 Kf = *(const LAS bf16x8*)(KL + (kb * 16 + fr) * 136 + ks * 32 + fq * 8);
;                 sa[kb] = __builtin_amdgcn_mfma_f32_16x16x32_bf16(Qf[ks], Kf, sa[kb], 0, 0, 0);
;             }
;         }
;         float mx[4] = {-3.0e38f, -3.0e38f, -3.0e38f, -3.0e38f};
; #pragma unroll
;         for (int kb = 0; kb < 16; ++kb)
; #pragma unroll
;             for (int j = 0; j < 4; ++j) {
;                 const int diff = (wid * 16 + fq * 4 + j) + 128 - kb * 16 - fr;
;                 const int kk = i0 - 128 + kb * 16 + fr;
;                 const bool valid = (kk >= 0) && (diff >= 0) && (diff <= 128);
;                 const float s = valid ? sa[kb][j] * scale : -1.0e30f;
;                 sa[kb][j] = s; mx[j] = fmaxf(mx[j], s);
;             }
	v_mfma_f32_16x16x32_bf16 v[60:63], v[32:35], v[40:43], v[36:39]
	ds_read_b128 v[40:43], v139 offset:39232
	s_nop 3
	ds_read_b128 v[36:39], v139 offset:39168
	s_waitcnt lgkmcnt(0)
	v_mfma_f32_16x16x32_bf16 v[36:39], v[96:99], v[36:39], 0
	v_mul_f32_e32 v60, 0x3db504f3, v60
	v_mfma_f32_16x16x32_bf16 v[36:39], v[92:95], v[40:43], v[36:39]
	ds_read_b128 v[40:43], v139 offset:39296
	s_waitcnt lgkmcnt(0)
	v_mfma_f32_16x16x32_bf16 v[36:39], v[88:91], v[40:43], v[36:39]
	ds_read_b128 v[40:43], v139 offset:39360
	s_waitcnt lgkmcnt(0)
	v_mfma_f32_16x16x32_bf16 v[56:59], v[32:35], v[40:43], v[36:39]
	ds_read_b128 v[40:43], v139 offset:43584
	s_nop 3
	ds_read_b128 v[36:39], v139 offset:43520
	s_waitcnt lgkmcnt(0)
	v_mfma_f32_16x16x32_bf16 v[36:39], v[96:99], v[36:39], 0
	v_mul_f32_e32 v56, 0x3db504f3, v56
	v_mul_f32_e32 v57, 0x3db504f3, v57
	v_mfma_f32_16x16x32_bf16 v[36:39], v[92:95], v[40:43], v[36:39]
	ds_read_b128 v[40:43], v139 offset:43648
	s_waitcnt lgkmcnt(0)
	v_mfma_f32_16x16x32_bf16 v[36:39], v[88:91], v[40:43], v[36:39]
	ds_read_b128 v[40:43], v139 offset:43712
	s_waitcnt lgkmcnt(0)
	v_mfma_f32_16x16x32_bf16 v[52:55], v[32:35], v[40:43], v[36:39]
	ds_read_b128 v[40:43], v139 offset:47936
	s_nop 3
	ds_read_b128 v[36:39], v139 offset:47872
	s_waitcnt lgkmcnt(0)
	v_mfma_f32_16x16x32_bf16 v[36:39], v[96:99], v[36:39], 0
	v_mul_f32_e32 v52, 0x3db504f3, v52
	v_mfma_f32_16x16x32_bf16 v[36:39], v[92:95], v[40:43], v[36:39]
	ds_read_b128 v[40:43], v139 offset:48000
	s_waitcnt lgkmcnt(0)
	v_mfma_f32_16x16x32_bf16 v[36:39], v[88:91], v[40:43], v[36:39]
	ds_read_b128 v[40:43], v139 offset:48064
	s_waitcnt lgkmcnt(0)
	v_mfma_f32_16x16x32_bf16 v[48:51], v[32:35], v[40:43], v[36:39]
	ds_read_b128 v[40:43], v139 offset:52288
	s_nop 3
	ds_read_b128 v[36:39], v139 offset:52224
	s_waitcnt lgkmcnt(0)
	v_mfma_f32_16x16x32_bf16 v[36:39], v[96:99], v[36:39], 0
	v_mul_f32_e32 v48, 0x3db504f3, v48
	v_mul_f32_e32 v49, 0x3db504f3, v49
	v_mfma_f32_16x16x32_bf16 v[36:39], v[92:95], v[40:43], v[36:39]
	ds_read_b128 v[40:43], v139 offset:52352
	s_waitcnt lgkmcnt(0)
	v_mfma_f32_16x16x32_bf16 v[36:39], v[88:91], v[40:43], v[36:39]
	ds_read_b128 v[40:43], v139 offset:52416
	s_waitcnt lgkmcnt(0)
	v_mfma_f32_16x16x32_bf16 v[44:47], v[32:35], v[40:43], v[36:39]
	ds_read_b128 v[40:43], v139 offset:56640
	s_nop 3
	ds_read_b128 v[36:39], v139 offset:56576
	s_waitcnt lgkmcnt(0)
	v_mfma_f32_16x16x32_bf16 v[36:39], v[96:99], v[36:39], 0
	v_mul_f32_e32 v44, 0x3db504f3, v44
	v_mfma_f32_16x16x32_bf16 v[36:39], v[92:95], v[40:43], v[36:39]
	ds_read_b128 v[40:43], v139 offset:56704
	s_waitcnt lgkmcnt(0)
	v_mfma_f32_16x16x32_bf16 v[36:39], v[88:91], v[40:43], v[36:39]
	ds_read_b128 v[40:43], v139 offset:56768
	s_waitcnt lgkmcnt(0)
	v_mfma_f32_16x16x32_bf16 v[40:43], v[32:35], v[40:43], v[36:39]
	s_nop 4
	ds_read_b128 v[36:39], v139 offset:60928
	s_waitcnt lgkmcnt(0)
	v_mfma_f32_16x16x32_bf16 v[36:39], v[96:99], v[36:39], 0
	v_mul_f32_e32 v40, 0x3db504f3, v40
	v_mul_f32_e32 v41, 0x3db504f3, v41
	v_mfma_f32_16x16x32_bf16 v[36:39], v[92:95], v[144:147], v[36:39]
	ds_read_b128 v[144:147], v139 offset:61056
	s_waitcnt lgkmcnt(0)
	v_mfma_f32_16x16x32_bf16 v[36:39], v[88:91], v[144:147], v[36:39]
	ds_read_b128 v[144:147], v139 offset:61120
	s_waitcnt lgkmcnt(0)
	v_mfma_f32_16x16x32_bf16 v[36:39], v[32:35], v[144:147], v[36:39]
	ds_read_b128 v[144:147], v139 offset:65280
	s_waitcnt lgkmcnt(0)
	v_mfma_f32_16x16x32_bf16 v[96:99], v[96:99], v[144:147], 0
	ds_read_b128 v[144:147], v139 offset:65344
	s_nop 3
	v_mul_f32_e32 v36, 0x3db504f3, v36
	s_waitcnt lgkmcnt(0)
	v_mfma_f32_16x16x32_bf16 v[92:95], v[92:95], v[144:147], v[96:99]
	s_nop 2
	ds_read_b128 v[96:99], v139 offset:65408
	s_waitcnt lgkmcnt(0)
	v_mfma_f32_16x16x32_bf16 v[88:91], v[88:91], v[96:99], v[92:95]
	s_nop 2
	ds_read_b128 v[92:95], v139 offset:65472
	s_waitcnt lgkmcnt(0)
	v_mfma_f32_16x16x32_bf16 v[32:35], v[32:35], v[92:95], v[88:91]
	v_mul_f32_e32 v93, 0x3db504f3, v102
	s_nop 1
	v_mul_f32_e32 v88, 0x3db504f3, v104
	v_cndmask_b32_e32 v90, v204, v88, vcc
	s_and_b64 vcc, s[40:41], s[78:79]
	v_readlane_b32 s78, v239, 46
	v_mul_f32_e32 v88, 0x3db504f3, v105
	v_readlane_b32 s79, v239, 47
	v_cndmask_b32_e32 v91, v204, v88, vcc
	s_and_b64 vcc, s[40:41], s[78:79]
	v_readlane_b32 s78, v239, 48
	v_mul_f32_e32 v88, 0x3db504f3, v106
	v_readlane_b32 s79, v239, 49
	v_cndmask_b32_e32 v92, v204, v88, vcc
	s_and_b64 vcc, s[40:41], s[78:79]
	v_readlane_b32 s78, v239, 50
	v_mul_f32_e32 v88, 0x3db504f3, v107
	v_readlane_b32 s79, v239, 51
	v_cndmask_b32_e32 v94, v204, v88, vcc
	s_and_b64 vcc, s[40:41], s[78:79]
	v_readlane_b32 s78, v239, 52
	v_mul_f32_e32 v88, 0x3db504f3, v100
	v_readlane_b32 s79, v239, 53
	v_cndmask_b32_e32 v88, v204, v88, vcc
	s_and_b64 vcc, s[40:41], s[78:79]
	v_readlane_b32 s78, v239, 54
	v_mul_f32_e32 v89, 0x3db504f3, v101
	v_readlane_b32 s79, v239, 55
	v_cndmask_b32_e32 v89, v204, v89, vcc
	s_and_b64 vcc, s[40:41], s[78:79]
	v_readlane_b32 s78, v239, 56
	v_readlane_b32 s79, v239, 57
	v_cndmask_b32_e32 v93, v204, v93, vcc
	s_and_b64 vcc, s[40:41], s[78:79]
	v_readlane_b32 s78, v239, 58
	v_mul_f32_e32 v95, 0x3db504f3, v103
	v_readlane_b32 s79, v239, 59
	v_cndmask_b32_e32 v95, v204, v95, vcc
	s_and_b64 vcc, s[40:41], s[78:79]
	v_readlane_b32 s78, v239, 60
	v_readlane_b32 s79, v239, 61
	v_cndmask_b32_e32 v84, v204, v84, vcc
	s_and_b64 vcc, s[40:41], s[78:79]
	v_readlane_b32 s78, v239, 62
	v_readlane_b32 s79, v239, 63
	v_cndmask_b32_e32 v85, v204, v85, vcc
	s_and_b64 vcc, s[40:41], s[78:79]
	v_readlane_b32 s78, v238, 0
	v_readlane_b32 s79, v238, 1
	v_cndmask_b32_e32 v86, v204, v86, vcc
	s_and_b64 vcc, s[40:41], s[78:79]
; __device__ __forceinline__ void attn_phase(const Params& p, LAS unsigned char* lds) {
;     ...
;         float mx[4] = {-3.0e38f, -3.0e38f, -3.0e38f, -3.0e38f};
; #pragma unroll
;         for (int kb = 0; kb < 16; ++kb)
; #pragma unroll
;             for (int j = 0; j < 4; ++j) {
;                 const int diff = (wid * 16 + fq * 4 + j) + 128 - kb * 16 - fr;
;                 const int kk = i0 - 128 + kb * 16 + fr;
;                 const bool valid = (kk >= 0) && (diff >= 0) && (diff <= 128);
;                 const float s = valid ? sa[kb][j] * scale : -1.0e30f;
;                 sa[kb][j] = s; mx[j] = fmaxf(mx[j], s);
;             }
; #pragma unroll
;         for (int j = 0; j < 4; ++j) {
; #pragma unroll
;             for (int o = 1; o < 16; o <<= 1) mx[j] = fmaxf(mx[j], __shfl_xor(mx[j], o));
	v_readlane_b32 s78, v238, 2
	v_readlane_b32 s79, v238, 3
	v_cndmask_b32_e32 v87, v204, v87, vcc
	s_and_b64 vcc, s[40:41], s[78:79]
	v_readlane_b32 s78, v238, 4
	v_readlane_b32 s79, v238, 5
	v_cndmask_b32_e32 v80, v204, v80, vcc
	s_and_b64 vcc, s[40:41], s[78:79]
	v_readlane_b32 s78, v238, 6
	v_readlane_b32 s79, v238, 7
	v_cndmask_b32_e32 v81, v204, v81, vcc
	s_and_b64 vcc, s[40:41], s[78:79]
	v_readlane_b32 s78, v238, 8
	v_readlane_b32 s79, v238, 9
	v_cndmask_b32_e32 v82, v204, v82, vcc
	s_and_b64 vcc, s[40:41], s[78:79]
	v_readlane_b32 s78, v238, 10
	v_readlane_b32 s79, v238, 11
	v_cndmask_b32_e32 v83, v204, v83, vcc
	s_and_b64 vcc, s[40:41], s[78:79]
	v_readlane_b32 s78, v238, 12
	v_readlane_b32 s79, v238, 13
	v_cndmask_b32_e32 v76, v204, v76, vcc
	s_and_b64 vcc, s[40:41], s[78:79]
	v_readlane_b32 s78, v238, 14
	v_readlane_b32 s79, v238, 15
	v_cndmask_b32_e32 v77, v204, v77, vcc
	s_and_b64 vcc, s[40:41], s[78:79]
	v_readlane_b32 s78, v238, 16
	v_readlane_b32 s79, v238, 17
	v_cndmask_b32_e32 v78, v204, v78, vcc
	s_and_b64 vcc, s[40:41], s[78:79]
	v_readlane_b32 s78, v238, 18
	v_readlane_b32 s79, v238, 19
	v_cndmask_b32_e32 v79, v204, v79, vcc
	s_and_b64 vcc, s[40:41], s[78:79]
	v_readlane_b32 s78, v238, 20
	v_readlane_b32 s79, v238, 21
	v_cndmask_b32_e32 v72, v204, v72, vcc
	s_and_b64 vcc, s[40:41], s[78:79]
	v_readlane_b32 s78, v238, 22
	v_readlane_b32 s79, v238, 23
	v_cndmask_b32_e32 v73, v204, v73, vcc
	s_and_b64 vcc, s[40:41], s[78:79]
	v_readlane_b32 s78, v238, 24
	v_readlane_b32 s79, v238, 25
	v_cndmask_b32_e32 v74, v204, v74, vcc
	s_and_b64 vcc, s[40:41], s[78:79]
	v_readlane_b32 s78, v238, 26
	v_readlane_b32 s79, v238, 27
	v_cndmask_b32_e32 v75, v204, v75, vcc
	s_and_b64 vcc, s[40:41], s[78:79]
	v_readlane_b32 s78, v238, 28
	v_readlane_b32 s79, v238, 29
	v_cndmask_b32_e32 v68, v204, v68, vcc
	s_and_b64 vcc, s[40:41], s[78:79]
	v_readlane_b32 s78, v238, 30
	v_readlane_b32 s79, v238, 31
	v_cndmask_b32_e32 v69, v204, v69, vcc
	s_and_b64 vcc, s[40:41], s[78:79]
	v_readlane_b32 s78, v238, 32
	v_readlane_b32 s79, v238, 33
	v_cndmask_b32_e32 v70, v204, v70, vcc
	s_and_b64 vcc, s[40:41], s[78:79]
	v_readlane_b32 s78, v238, 34
	v_readlane_b32 s79, v238, 35
	v_cndmask_b32_e32 v71, v204, v71, vcc
	s_and_b64 vcc, s[40:41], s[78:79]
	v_readlane_b32 s78, v238, 36
	v_readlane_b32 s79, v238, 37
	v_cndmask_b32_e32 v64, v204, v64, vcc
	s_and_b64 vcc, s[40:41], s[78:79]
	v_readlane_b32 s78, v238, 38
	v_readlane_b32 s79, v238, 39
	v_cndmask_b32_e32 v65, v204, v65, vcc
	s_and_b64 vcc, s[40:41], s[78:79]
	v_readlane_b32 s78, v238, 40
	v_readlane_b32 s79, v238, 41
	v_cndmask_b32_e32 v66, v204, v66, vcc
	s_and_b64 vcc, s[40:41], s[78:79]
	v_readlane_b32 s40, v238, 42
	v_max3_f32 v96, v90, s33, v88
	v_max3_f32 v97, v91, s33, v89
	v_readlane_b32 s41, v238, 43
	v_max3_f32 v96, v96, v84, v80
	v_max3_f32 v97, v97, v85, v81
	v_cndmask_b32_e64 v101, v204, v60, s[40:41]
	v_readlane_b32 s40, v238, 44
	v_max3_f32 v99, v94, s33, v95
	v_max3_f32 v96, v96, v76, v72
	v_max3_f32 v97, v97, v77, v73
	v_mul_f32_e32 v60, 0x3db504f3, v61
	v_readlane_b32 s41, v238, 45
	v_max3_f32 v99, v99, v87, v83
	v_max3_f32 v96, v96, v68, v64
	v_max3_f32 v102, v97, v69, v65
	v_cndmask_b32_e64 v100, v204, v60, s[40:41]
	v_readlane_b32 s40, v238, 46
	v_cndmask_b32_e64 v97, v204, v56, s[52:53]
	v_max3_f32 v98, v92, s33, v93
	v_max3_f32 v99, v99, v79, v75
	v_cndmask_b32_e32 v67, v204, v67, vcc
	v_mul_f32_e32 v60, 0x3db504f3, v62
	v_readlane_b32 s41, v238, 47
	v_max3_f32 v56, v96, v101, v97
	v_cndmask_b32_e64 v96, v204, v57, s[54:55]
	v_mul_f32_e32 v57, 0x3db504f3, v58
	v_max3_f32 v98, v98, v86, v82
	v_max3_f32 v104, v99, v71, v67
	v_cndmask_b32_e64 v99, v204, v60, s[40:41]
	v_mul_f32_e32 v60, 0x3db504f3, v63
	v_cndmask_b32_e64 v63, v204, v57, s[56:57]
	v_mul_f32_e32 v57, 0x3db504f3, v59
	v_max3_f32 v98, v98, v78, v74
	v_cndmask_b32_e64 v62, v204, v57, s[58:59]
	v_cndmask_b32_e64 v61, v204, v52, s[60:61]
	v_mul_f32_e32 v52, 0x3db504f3, v53
	v_cndmask_b32_e64 v57, v204, v48, s[68:69]
	v_max3_f32 v103, v98, v70, v66
	v_cndmask_b32_e64 v98, v204, v60, s[48:49]
	v_cndmask_b32_e64 v60, v204, v52, s[62:63]
	v_mul_f32_e32 v52, 0x3db504f3, v54
	v_max3_f32 v48, v56, v61, v57
	v_cndmask_b32_e64 v56, v204, v49, s[70:71]
	v_mul_f32_e32 v49, 0x3db504f3, v50
	v_cndmask_b32_e64 v59, v204, v52, s[64:65]
	v_mul_f32_e32 v52, 0x3db504f3, v55
	v_cndmask_b32_e64 v55, v204, v49, s[42:43]
	v_mul_f32_e32 v49, 0x3db504f3, v51
	v_cndmask_b32_e64 v53, v204, v44, s[0:1]
	v_mul_f32_e32 v44, 0x3db504f3, v45
	v_cndmask_b32_e64 v58, v204, v52, s[66:67]
	v_cndmask_b32_e64 v54, v204, v49, s[6:7]
	v_cndmask_b32_e64 v52, v204, v44, s[8:9]
	v_mul_f32_e32 v44, 0x3db504f3, v46
	v_cndmask_b32_e64 v49, v204, v40, s[14:15]
	v_cndmask_b32_e64 v51, v204, v44, s[10:11]
	v_mul_f32_e32 v44, 0x3db504f3, v47
	v_max3_f32 v40, v48, v53, v49
	v_cndmask_b32_e64 v48, v204, v41, s[16:17]
	v_mul_f32_e32 v41, 0x3db504f3, v42
	v_cndmask_b32_e64 v45, v204, v36, s[22:23]
	v_mul_f32_e32 v36, 0x3db504f3, v37
	v_cndmask_b32_e64 v50, v204, v44, s[12:13]
	v_cndmask_b32_e64 v47, v204, v41, s[18:19]
	v_mul_f32_e32 v41, 0x3db504f3, v43
	v_cndmask_b32_e64 v44, v204, v36, s[24:25]
	v_mul_f32_e32 v36, 0x3db504f3, v38
	v_mul_f32_e32 v32, 0x3db504f3, v32
	v_cndmask_b32_e64 v46, v204, v41, s[20:21]
	v_cndmask_b32_e64 v43, v204, v36, s[26:27]
	v_mul_f32_e32 v36, 0x3db504f3, v39
	v_cndmask_b32_e64 v41, v204, v32, s[30:31]
	v_cndmask_b32_e64 v42, v204, v36, s[28:29]
	v_max3_f32 v36, v40, v45, v41
	s_nop 1
	v_mov_b32_dpp v38, v36 quad_perm:[1,0,3,2] row_mask:0xf bank_mask:0xf
	v_max3_f32 v102, v102, v100, v96
	v_max3_f32 v102, v102, v60, v56
	v_mul_f32_e32 v32, 0x3db504f3, v33
	v_max3_f32 v102, v102, v52, v48
	s_waitcnt lgkmcnt(0)
; __device__ __forceinline__ bf16_t f2bf(float f) { return (bf16_t)(cvt_pk_bf16(f, 0.f) & 0xffffu); }
; __device__ __forceinline__ void attn_phase(const Params& p, LAS unsigned char* lds) {
;     ...
; #pragma unroll
;         for (int j = 0; j < 4; ++j) {
; #pragma unroll
;             for (int o = 1; o < 16; o <<= 1) mx[j] = fmaxf(mx[j], __shfl_xor(mx[j], o));
;         }
;         float ls[4] = {0.f, 0.f, 0.f, 0.f};
; #pragma unroll
;         for (int kb = 0; kb < 16; ++kb)
; #pragma unroll
;             for (int j = 0; j < 4; ++j) {
;                 const float pv = __expf(sa[kb][j] - mx[j]);
;                 ls[j] += pv;
;                 PLw[(fq * 4 + j) * 264 + kb * 16 + fr] = f2bf(pv);
;             }
	v_max_f32_e32 v38, v38, v38
	v_max_f32_e32 v36, v36, v38
	s_nop 1
	v_mov_b32_dpp v38, v36 quad_perm:[2,3,0,1] row_mask:0xf bank_mask:0xf
	v_cndmask_b32_e64 v40, v204, v32, s[34:35]
	v_max3_f32 v37, v102, v44, v40
	v_max3_f32 v103, v103, v99, v63
	v_max3_f32 v103, v103, v59, v55
	s_waitcnt lgkmcnt(0)
	v_max_f32_e32 v38, v38, v38
	v_max_f32_e32 v36, v36, v38
	s_nop 1
	v_mov_b32_dpp v38, v36 row_half_mirror row_mask:0xf bank_mask:0xf
	v_mul_f32_e32 v32, 0x3db504f3, v34
	v_max3_f32 v103, v103, v51, v47
	v_cndmask_b32_e64 v33, v204, v32, s[36:37]
	v_max3_f32 v34, v103, v43, v33
	s_waitcnt lgkmcnt(0)
	v_max_f32_e32 v38, v38, v38
	v_max_f32_e32 v36, v36, v38
	s_nop 1
	v_mov_b32_dpp v38, v36 row_mirror row_mask:0xf bank_mask:0xf
	v_max3_f32 v104, v104, v98, v62
	v_max3_f32 v104, v104, v58, v54
	v_mul_f32_e32 v32, 0x3db504f3, v35
	v_max3_f32 v104, v104, v50, v46
	s_waitcnt lgkmcnt(0)
	v_max_f32_e32 v38, v38, v38
	v_max_f32_e32 v39, v36, v38
	s_nop 1
	v_mov_b32_dpp v36, v37 quad_perm:[1,0,3,2] row_mask:0xf bank_mask:0xf
	v_cndmask_b32_e64 v32, v204, v32, s[38:39]
	v_max3_f32 v35, v104, v42, v32
	s_waitcnt lgkmcnt(0)
	v_max_f32_e32 v36, v36, v36
	v_max_f32_e32 v36, v37, v36
	s_nop 1
	v_mov_b32_dpp v37, v36 quad_perm:[2,3,0,1] row_mask:0xf bank_mask:0xf
	s_waitcnt lgkmcnt(0)
	v_max_f32_e32 v37, v37, v37
	v_max_f32_e32 v36, v36, v37
	s_nop 1
	v_mov_b32_dpp v37, v36 row_half_mirror row_mask:0xf bank_mask:0xf
	s_waitcnt lgkmcnt(0)
	v_max_f32_e32 v37, v37, v37
	v_max_f32_e32 v36, v36, v37
	s_nop 1
	v_mov_b32_dpp v37, v36 row_mirror row_mask:0xf bank_mask:0xf
	s_waitcnt lgkmcnt(0)
	v_max_f32_e32 v37, v37, v37
	v_max_f32_e32 v38, v36, v37
	s_nop 1
	v_mov_b32_dpp v36, v34 quad_perm:[1,0,3,2] row_mask:0xf bank_mask:0xf
	s_waitcnt lgkmcnt(0)
	v_max_f32_e32 v36, v36, v36
	v_max_f32_e32 v34, v34, v36
	s_nop 1
	v_mov_b32_dpp v36, v34 quad_perm:[2,3,0,1] row_mask:0xf bank_mask:0xf
	s_waitcnt lgkmcnt(0)
	v_max_f32_e32 v36, v36, v36
	v_max_f32_e32 v34, v34, v36
	s_nop 1
	v_mov_b32_dpp v36, v34 row_half_mirror row_mask:0xf bank_mask:0xf
	s_waitcnt lgkmcnt(0)
	v_max_f32_e32 v36, v36, v36
	v_max_f32_e32 v34, v34, v36
	s_nop 1
	v_mov_b32_dpp v36, v34 row_mirror row_mask:0xf bank_mask:0xf
	s_waitcnt lgkmcnt(0)
	v_max_f32_e32 v36, v36, v36
	v_max_f32_e32 v37, v34, v36
	s_nop 1
	v_mov_b32_dpp v34, v35 quad_perm:[1,0,3,2] row_mask:0xf bank_mask:0xf
	v_sub_f32_e32 v33, v33, v37
	v_mul_f32_e32 v33, 0x3fb8aa3b, v33
	v_exp_f32_e32 v33, v33
	s_waitcnt lgkmcnt(0)
	v_max_f32_e32 v34, v34, v34
	v_max_f32_e32 v34, v35, v34
	s_nop 1
	v_mov_b32_dpp v35, v34 quad_perm:[2,3,0,1] row_mask:0xf bank_mask:0xf
	s_waitcnt lgkmcnt(0)
	v_max_f32_e32 v35, v35, v35
	v_max_f32_e32 v34, v34, v35
	s_nop 1
	v_mov_b32_dpp v35, v34 row_half_mirror row_mask:0xf bank_mask:0xf
	s_waitcnt lgkmcnt(0)
	v_max_f32_e32 v35, v35, v35
	v_max_f32_e32 v34, v34, v35
	s_nop 1
	v_mov_b32_dpp v35, v34 row_mirror row_mask:0xf bank_mask:0xf
	s_waitcnt lgkmcnt(0)
	v_max_f32_e32 v35, v35, v35
	v_max_f32_e32 v36, v34, v35
	v_sub_f32_e32 v34, v90, v39
	v_mul_f32_e32 v34, 0x3fb8aa3b, v34
	v_exp_f32_e32 v34, v34
	v_sub_f32_e32 v32, v32, v36
	v_mul_f32_e32 v32, 0x3fb8aa3b, v32
	v_exp_f32_e32 v32, v32
	v_add_f32_e32 v35, 0, v34
	v_cvt_pk_bf16_f32 v34, v34, v169
	ds_write_b16 v130, v34
	v_sub_f32_e32 v34, v91, v38
	v_mul_f32_e32 v34, 0x3fb8aa3b, v34
	v_exp_f32_e32 v34, v34
	s_nop 0
	v_add_f32_e32 v90, 0, v34
	v_cvt_pk_bf16_f32 v34, v34, v169
	ds_write_b16 v130, v34 offset:528
	v_sub_f32_e32 v34, v92, v37
	v_mul_f32_e32 v34, 0x3fb8aa3b, v34
	v_exp_f32_e32 v34, v34
	s_nop 0
	v_add_f32_e32 v91, 0, v34
	v_cvt_pk_bf16_f32 v34, v34, v169
	ds_write_b16 v130, v34 offset:1056
	v_sub_f32_e32 v34, v94, v36
	v_mul_f32_e32 v34, 0x3fb8aa3b, v34
	v_exp_f32_e32 v34, v34
	s_nop 0
	v_add_f32_e32 v92, 0, v34
	v_cvt_pk_bf16_f32 v34, v34, v169
	ds_write_b16 v130, v34 offset:1584
	v_sub_f32_e32 v34, v88, v39
	v_mul_f32_e32 v34, 0x3fb8aa3b, v34
	v_exp_f32_e32 v34, v34
	s_nop 0
	v_add_f32_e32 v35, v34, v35
	v_cvt_pk_bf16_f32 v34, v34, v169
	ds_write_b16 v130, v34 offset:32
	v_sub_f32_e32 v34, v89, v38
	v_mul_f32_e32 v34, 0x3fb8aa3b, v34
	v_exp_f32_e32 v34, v34
	s_nop 0
	v_add_f32_e32 v88, v34, v90
	v_cvt_pk_bf16_f32 v34, v34, v169
	ds_write_b16 v130, v34 offset:560
	v_sub_f32_e32 v34, v93, v37
	v_mul_f32_e32 v34, 0x3fb8aa3b, v34
	v_exp_f32_e32 v34, v34
	s_nop 0
	v_add_f32_e32 v89, v34, v91
	v_cvt_pk_bf16_f32 v34, v34, v169
	ds_write_b16 v130, v34 offset:1088
	v_sub_f32_e32 v34, v95, v36
	v_mul_f32_e32 v34, 0x3fb8aa3b, v34
	v_exp_f32_e32 v34, v34
	s_nop 0
	v_add_f32_e32 v90, v34, v92
	v_cvt_pk_bf16_f32 v34, v34, v169
	ds_write_b16 v130, v34 offset:1616
	v_sub_f32_e32 v34, v84, v39
	v_mul_f32_e32 v34, 0x3fb8aa3b, v34
	v_exp_f32_e32 v34, v34
	s_nop 0
	v_add_f32_e32 v35, v34, v35
	v_cvt_pk_bf16_f32 v34, v34, v169
	ds_write_b16 v130, v34 offset:64
	v_sub_f32_e32 v34, v85, v38
	v_mul_f32_e32 v34, 0x3fb8aa3b, v34
	v_exp_f32_e32 v34, v34
	s_nop 0
	v_add_f32_e32 v84, v34, v88
	v_cvt_pk_bf16_f32 v34, v34, v169
	ds_write_b16 v130, v34 offset:592
	v_sub_f32_e32 v34, v86, v37
	v_mul_f32_e32 v34, 0x3fb8aa3b, v34
	v_exp_f32_e32 v34, v34
	s_nop 0
	v_add_f32_e32 v85, v34, v89
	v_cvt_pk_bf16_f32 v34, v34, v169
	ds_write_b16 v130, v34 offset:1120
	v_sub_f32_e32 v34, v87, v36
	v_mul_f32_e32 v34, 0x3fb8aa3b, v34
	v_exp_f32_e32 v34, v34
	s_nop 0
	v_add_f32_e32 v86, v34, v90
	v_cvt_pk_bf16_f32 v34, v34, v169
	ds_write_b16 v130, v34 offset:1648
	v_sub_f32_e32 v34, v80, v39
	v_mul_f32_e32 v34, 0x3fb8aa3b, v34
	v_exp_f32_e32 v34, v34
	s_nop 0
	v_add_f32_e32 v35, v34, v35
	v_cvt_pk_bf16_f32 v34, v34, v169
	ds_write_b16 v130, v34 offset:96
	v_sub_f32_e32 v34, v81, v38
; __device__ __forceinline__ bf16_t f2bf(float f) { return (bf16_t)(cvt_pk_bf16(f, 0.f) & 0xffffu); }
; __device__ __forceinline__ void attn_phase(const Params& p, LAS unsigned char* lds) {
;     ...
;         float ls[4] = {0.f, 0.f, 0.f, 0.f};
; #pragma unroll
;         for (int kb = 0; kb < 16; ++kb)
; #pragma unroll
;             for (int j = 0; j < 4; ++j) {
;                 const float pv = __expf(sa[kb][j] - mx[j]);
;                 ls[j] += pv;
;                 PLw[(fq * 4 + j) * 264 + kb * 16 + fr] = f2bf(pv);
;             }
	v_mul_f32_e32 v34, 0x3fb8aa3b, v34
	v_exp_f32_e32 v34, v34
	s_nop 0
	v_add_f32_e32 v80, v34, v84
	v_cvt_pk_bf16_f32 v34, v34, v169
	ds_write_b16 v130, v34 offset:624
	v_sub_f32_e32 v34, v82, v37
	v_mul_f32_e32 v34, 0x3fb8aa3b, v34
	v_exp_f32_e32 v34, v34
	s_nop 0
	v_add_f32_e32 v81, v34, v85
	v_cvt_pk_bf16_f32 v34, v34, v169
	ds_write_b16 v130, v34 offset:1152
	v_sub_f32_e32 v34, v83, v36
	v_mul_f32_e32 v34, 0x3fb8aa3b, v34
	v_exp_f32_e32 v34, v34
	s_nop 0
	v_add_f32_e32 v82, v34, v86
	v_cvt_pk_bf16_f32 v34, v34, v169
	ds_write_b16 v130, v34 offset:1680
	v_sub_f32_e32 v34, v76, v39
	v_mul_f32_e32 v34, 0x3fb8aa3b, v34
	v_exp_f32_e32 v34, v34
	s_nop 0
	v_add_f32_e32 v35, v34, v35
	v_cvt_pk_bf16_f32 v34, v34, v169
	ds_write_b16 v130, v34 offset:128
	v_sub_f32_e32 v34, v77, v38
	v_mul_f32_e32 v34, 0x3fb8aa3b, v34
	v_exp_f32_e32 v34, v34
	s_nop 0
	v_add_f32_e32 v76, v34, v80
	v_cvt_pk_bf16_f32 v34, v34, v169
	ds_write_b16 v130, v34 offset:656
	v_sub_f32_e32 v34, v78, v37
	v_mul_f32_e32 v34, 0x3fb8aa3b, v34
	v_exp_f32_e32 v34, v34
	s_nop 0
	v_add_f32_e32 v77, v34, v81
	v_cvt_pk_bf16_f32 v34, v34, v169
	ds_write_b16 v130, v34 offset:1184
	v_sub_f32_e32 v34, v79, v36
	v_mul_f32_e32 v34, 0x3fb8aa3b, v34
	v_exp_f32_e32 v34, v34
	s_nop 0
	v_add_f32_e32 v78, v34, v82
	v_cvt_pk_bf16_f32 v34, v34, v169
	ds_write_b16 v130, v34 offset:1712
	v_sub_f32_e32 v34, v72, v39
	v_mul_f32_e32 v34, 0x3fb8aa3b, v34
	v_exp_f32_e32 v34, v34
	s_nop 0
	v_add_f32_e32 v35, v34, v35
	v_cvt_pk_bf16_f32 v34, v34, v169
	ds_write_b16 v130, v34 offset:160
	v_sub_f32_e32 v34, v73, v38
	v_mul_f32_e32 v34, 0x3fb8aa3b, v34
	v_exp_f32_e32 v34, v34
	s_nop 0
	v_add_f32_e32 v72, v34, v76
	v_cvt_pk_bf16_f32 v34, v34, v169
	ds_write_b16 v130, v34 offset:688
	v_sub_f32_e32 v34, v74, v37
	v_mul_f32_e32 v34, 0x3fb8aa3b, v34
	v_exp_f32_e32 v34, v34
	s_nop 0
	v_add_f32_e32 v73, v34, v77
	v_cvt_pk_bf16_f32 v34, v34, v169
	ds_write_b16 v130, v34 offset:1216
	v_sub_f32_e32 v34, v75, v36
	v_mul_f32_e32 v34, 0x3fb8aa3b, v34
	v_exp_f32_e32 v34, v34
	s_nop 0
	v_add_f32_e32 v74, v34, v78
	v_cvt_pk_bf16_f32 v34, v34, v169
	ds_write_b16 v130, v34 offset:1744
	v_sub_f32_e32 v34, v68, v39
	v_mul_f32_e32 v34, 0x3fb8aa3b, v34
	v_exp_f32_e32 v34, v34
	s_nop 0
	v_add_f32_e32 v35, v34, v35
	v_cvt_pk_bf16_f32 v34, v34, v169
	ds_write_b16 v130, v34 offset:192
	v_sub_f32_e32 v34, v69, v38
	v_mul_f32_e32 v34, 0x3fb8aa3b, v34
	v_exp_f32_e32 v34, v34
	s_nop 0
	v_add_f32_e32 v68, v34, v72
	v_cvt_pk_bf16_f32 v34, v34, v169
	ds_write_b16 v130, v34 offset:720
	v_sub_f32_e32 v34, v70, v37
	v_mul_f32_e32 v34, 0x3fb8aa3b, v34
	v_exp_f32_e32 v34, v34
	s_nop 0
	v_add_f32_e32 v69, v34, v73
	v_cvt_pk_bf16_f32 v34, v34, v169
	ds_write_b16 v130, v34 offset:1248
	v_sub_f32_e32 v34, v71, v36
	v_mul_f32_e32 v34, 0x3fb8aa3b, v34
	v_exp_f32_e32 v34, v34
	s_nop 0
	v_add_f32_e32 v70, v34, v74
	v_cvt_pk_bf16_f32 v34, v34, v169
	ds_write_b16 v130, v34 offset:1776
	v_sub_f32_e32 v34, v64, v39
	v_mul_f32_e32 v34, 0x3fb8aa3b, v34
	v_exp_f32_e32 v34, v34
	s_nop 0
	v_add_f32_e32 v35, v34, v35
	v_cvt_pk_bf16_f32 v34, v34, v169
	ds_write_b16 v130, v34 offset:224
	v_sub_f32_e32 v34, v65, v38
	v_mul_f32_e32 v34, 0x3fb8aa3b, v34
	v_exp_f32_e32 v34, v34
	s_nop 0
	v_add_f32_e32 v64, v34, v68
	v_cvt_pk_bf16_f32 v34, v34, v169
	ds_write_b16 v130, v34 offset:752
	v_sub_f32_e32 v34, v66, v37
	v_mul_f32_e32 v34, 0x3fb8aa3b, v34
	v_exp_f32_e32 v34, v34
	s_nop 0
	v_add_f32_e32 v65, v34, v69
	v_cvt_pk_bf16_f32 v34, v34, v169
	ds_write_b16 v130, v34 offset:1280
	v_sub_f32_e32 v34, v67, v36
	v_mul_f32_e32 v34, 0x3fb8aa3b, v34
	v_exp_f32_e32 v34, v34
	s_nop 0
	v_add_f32_e32 v66, v34, v70
	v_cvt_pk_bf16_f32 v34, v34, v169
	ds_write_b16 v130, v34 offset:1808
	v_sub_f32_e32 v34, v101, v39
	v_mul_f32_e32 v34, 0x3fb8aa3b, v34
	v_exp_f32_e32 v34, v34
	s_nop 0
	v_add_f32_e32 v35, v34, v35
	v_cvt_pk_bf16_f32 v34, v34, v169
	ds_write_b16 v130, v34 offset:256
	v_sub_f32_e32 v34, v100, v38
	v_mul_f32_e32 v34, 0x3fb8aa3b, v34
	v_exp_f32_e32 v34, v34
	s_nop 0
	v_add_f32_e32 v64, v34, v64
	v_cvt_pk_bf16_f32 v34, v34, v169
	ds_write_b16 v130, v34 offset:784
	v_sub_f32_e32 v34, v99, v37
	v_mul_f32_e32 v34, 0x3fb8aa3b, v34
	v_exp_f32_e32 v34, v34
	s_nop 0
	v_add_f32_e32 v65, v34, v65
	v_cvt_pk_bf16_f32 v34, v34, v169
	ds_write_b16 v130, v34 offset:1312
	v_sub_f32_e32 v34, v98, v36
	v_mul_f32_e32 v34, 0x3fb8aa3b, v34
	v_exp_f32_e32 v34, v34
	s_nop 0
	v_add_f32_e32 v66, v34, v66
	v_cvt_pk_bf16_f32 v34, v34, v169
	ds_write_b16 v130, v34 offset:1840
	v_sub_f32_e32 v34, v97, v39
	v_mul_f32_e32 v34, 0x3fb8aa3b, v34
	v_exp_f32_e32 v34, v34
	s_nop 0
	v_add_f32_e32 v35, v34, v35
	v_cvt_pk_bf16_f32 v34, v34, v169
	ds_write_b16 v130, v34 offset:288
	v_sub_f32_e32 v34, v96, v38
	v_mul_f32_e32 v34, 0x3fb8aa3b, v34
	v_exp_f32_e32 v34, v34
	s_nop 0
	v_add_f32_e32 v64, v34, v64
	v_cvt_pk_bf16_f32 v34, v34, v169
	ds_write_b16 v130, v34 offset:816
	v_sub_f32_e32 v34, v63, v37
	v_mul_f32_e32 v34, 0x3fb8aa3b, v34
	v_exp_f32_e32 v34, v34
	s_nop 0
	v_add_f32_e32 v63, v34, v65
	v_cvt_pk_bf16_f32 v34, v34, v169
	ds_write_b16 v130, v34 offset:1344
	v_sub_f32_e32 v34, v62, v36
	v_mul_f32_e32 v34, 0x3fb8aa3b, v34
	v_exp_f32_e32 v34, v34
	s_nop 0
	v_add_f32_e32 v62, v34, v66
	v_cvt_pk_bf16_f32 v34, v34, v169
	ds_write_b16 v130, v34 offset:1872
	v_sub_f32_e32 v34, v61, v39
	v_mul_f32_e32 v34, 0x3fb8aa3b, v34
	v_exp_f32_e32 v34, v34
	s_nop 0
	v_add_f32_e32 v35, v34, v35
	v_cvt_pk_bf16_f32 v34, v34, v169
	ds_write_b16 v130, v34 offset:320
	v_sub_f32_e32 v34, v60, v38
	v_mul_f32_e32 v34, 0x3fb8aa3b, v34
	v_exp_f32_e32 v34, v34
	s_nop 0
	v_add_f32_e32 v60, v34, v64
	v_cvt_pk_bf16_f32 v34, v34, v169
; __device__ __forceinline__ bf16_t f2bf(float f) { return (bf16_t)(cvt_pk_bf16(f, 0.f) & 0xffffu); }
; __device__ __forceinline__ void attn_phase(const Params& p, LAS unsigned char* lds) {
;     ...
;         float ls[4] = {0.f, 0.f, 0.f, 0.f};
; #pragma unroll
;         for (int kb = 0; kb < 16; ++kb)
; #pragma unroll
;             for (int j = 0; j < 4; ++j) {
;                 const float pv = __expf(sa[kb][j] - mx[j]);
;                 ls[j] += pv;
;                 PLw[(fq * 4 + j) * 264 + kb * 16 + fr] = f2bf(pv);
;             }
; #pragma unroll
;         for (int j = 0; j < 4; ++j) {
; #pragma unroll
;             for (int o = 1; o < 16; o <<= 1) ls[j] += __shfl_xor(ls[j], o);
;         }
;         __syncthreads();
	ds_write_b16 v130, v34 offset:848
	v_sub_f32_e32 v34, v59, v37
	v_mul_f32_e32 v34, 0x3fb8aa3b, v34
	v_exp_f32_e32 v34, v34
	s_nop 0
	v_add_f32_e32 v59, v34, v63
	v_cvt_pk_bf16_f32 v34, v34, v169
	ds_write_b16 v130, v34 offset:1376
	v_sub_f32_e32 v34, v58, v36
	v_mul_f32_e32 v34, 0x3fb8aa3b, v34
	v_exp_f32_e32 v34, v34
	s_nop 0
	v_add_f32_e32 v58, v34, v62
	v_cvt_pk_bf16_f32 v34, v34, v169
	ds_write_b16 v130, v34 offset:1904
	v_sub_f32_e32 v34, v57, v39
	v_mul_f32_e32 v34, 0x3fb8aa3b, v34
	v_exp_f32_e32 v34, v34
	s_nop 0
	v_add_f32_e32 v35, v34, v35
	v_cvt_pk_bf16_f32 v34, v34, v169
	ds_write_b16 v130, v34 offset:352
	v_sub_f32_e32 v34, v56, v38
	v_mul_f32_e32 v34, 0x3fb8aa3b, v34
	v_exp_f32_e32 v34, v34
	s_nop 0
	v_add_f32_e32 v56, v34, v60
	v_cvt_pk_bf16_f32 v34, v34, v169
	ds_write_b16 v130, v34 offset:880
	v_sub_f32_e32 v34, v55, v37
	v_mul_f32_e32 v34, 0x3fb8aa3b, v34
	v_exp_f32_e32 v34, v34
	s_nop 0
	v_add_f32_e32 v55, v34, v59
	v_cvt_pk_bf16_f32 v34, v34, v169
	ds_write_b16 v130, v34 offset:1408
	v_sub_f32_e32 v34, v54, v36
	v_mul_f32_e32 v34, 0x3fb8aa3b, v34
	v_exp_f32_e32 v34, v34
	s_nop 0
	v_add_f32_e32 v54, v34, v58
	v_cvt_pk_bf16_f32 v34, v34, v169
	ds_write_b16 v130, v34 offset:1936
	v_sub_f32_e32 v34, v53, v39
	v_mul_f32_e32 v34, 0x3fb8aa3b, v34
	v_exp_f32_e32 v34, v34
	s_nop 0
	v_add_f32_e32 v35, v34, v35
	v_cvt_pk_bf16_f32 v34, v34, v169
	ds_write_b16 v130, v34 offset:384
	v_sub_f32_e32 v34, v52, v38
	v_mul_f32_e32 v34, 0x3fb8aa3b, v34
	v_exp_f32_e32 v34, v34
	s_nop 0
	v_add_f32_e32 v52, v34, v56
	v_cvt_pk_bf16_f32 v34, v34, v169
	ds_write_b16 v130, v34 offset:912
	v_sub_f32_e32 v34, v51, v37
	v_mul_f32_e32 v34, 0x3fb8aa3b, v34
	v_exp_f32_e32 v34, v34
	s_nop 0
	v_add_f32_e32 v51, v34, v55
	v_cvt_pk_bf16_f32 v34, v34, v169
	ds_write_b16 v130, v34 offset:1440
	v_sub_f32_e32 v34, v50, v36
	v_mul_f32_e32 v34, 0x3fb8aa3b, v34
	v_exp_f32_e32 v34, v34
	s_nop 0
	v_add_f32_e32 v50, v34, v54
	v_cvt_pk_bf16_f32 v34, v34, v169
	ds_write_b16 v130, v34 offset:1968
	v_sub_f32_e32 v34, v49, v39
	v_mul_f32_e32 v34, 0x3fb8aa3b, v34
	v_exp_f32_e32 v34, v34
	s_nop 0
	v_add_f32_e32 v35, v34, v35
	v_cvt_pk_bf16_f32 v34, v34, v169
	ds_write_b16 v130, v34 offset:416
	v_sub_f32_e32 v34, v48, v38
	v_mul_f32_e32 v34, 0x3fb8aa3b, v34
	v_exp_f32_e32 v34, v34
	s_nop 0
	v_add_f32_e32 v48, v34, v52
	v_cvt_pk_bf16_f32 v34, v34, v169
	ds_write_b16 v130, v34 offset:944
	v_sub_f32_e32 v34, v47, v37
	v_mul_f32_e32 v34, 0x3fb8aa3b, v34
	v_exp_f32_e32 v34, v34
	s_nop 0
	v_add_f32_e32 v47, v34, v51
	v_cvt_pk_bf16_f32 v34, v34, v169
	ds_write_b16 v130, v34 offset:1472
	v_sub_f32_e32 v34, v46, v36
	v_mul_f32_e32 v34, 0x3fb8aa3b, v34
	v_exp_f32_e32 v34, v34
	s_nop 0
	v_add_f32_e32 v46, v34, v50
	v_cvt_pk_bf16_f32 v34, v34, v169
	ds_write_b16 v130, v34 offset:2000
	v_sub_f32_e32 v34, v45, v39
	v_mul_f32_e32 v34, 0x3fb8aa3b, v34
	v_exp_f32_e32 v34, v34
	s_nop 0
	v_add_f32_e32 v35, v34, v35
	v_cvt_pk_bf16_f32 v34, v34, v169
	ds_write_b16 v130, v34 offset:448
	v_sub_f32_e32 v34, v44, v38
	v_mul_f32_e32 v34, 0x3fb8aa3b, v34
	v_exp_f32_e32 v34, v34
	s_nop 0
	v_add_f32_e32 v44, v34, v48
	v_cvt_pk_bf16_f32 v34, v34, v169
	ds_write_b16 v130, v34 offset:976
	v_sub_f32_e32 v34, v43, v37
	v_mul_f32_e32 v34, 0x3fb8aa3b, v34
	v_exp_f32_e32 v34, v34
	s_nop 0
	v_add_f32_e32 v43, v34, v47
	v_cvt_pk_bf16_f32 v34, v34, v169
	ds_write_b16 v130, v34 offset:1504
	v_sub_f32_e32 v34, v42, v36
	v_mul_f32_e32 v34, 0x3fb8aa3b, v34
	v_exp_f32_e32 v34, v34
	v_add_u32_e32 v47, v114, v116
	v_add_f32_e32 v42, v34, v46
	v_cvt_pk_bf16_f32 v34, v34, v169
	ds_write_b16 v130, v34 offset:2032
	v_sub_f32_e32 v34, v41, v39
	v_mul_f32_e32 v34, 0x3fb8aa3b, v34
	v_exp_f32_e32 v34, v34
	s_nop 0
	v_add_f32_e32 v35, v34, v35
	v_cvt_pk_bf16_f32 v34, v34, v169
	ds_write_b16 v130, v34 offset:480
	v_sub_f32_e32 v34, v40, v38
	v_mul_f32_e32 v34, 0x3fb8aa3b, v34
	v_exp_f32_e32 v34, v34
	s_nop 0
	v_add_f32_e32 v40, v34, v44
	v_cvt_pk_bf16_f32 v34, v34, v169
	ds_write_b16 v130, v34 offset:1008
	v_add_f32_e32 v34, v33, v43
	v_cvt_pk_bf16_f32 v33, v33, v169
	ds_write_b16 v130, v33 offset:1536
	v_add_f32_e32 v33, v32, v42
	v_cvt_pk_bf16_f32 v32, v32, v169
	ds_write_b16 v130, v32 offset:2064
	s_nop 1
	v_mov_b32_dpp v32, v35 quad_perm:[1,0,3,2] row_mask:0xf bank_mask:0xf
	s_waitcnt lgkmcnt(0)
	s_barrier
; #define LAS __attribute__((address_space(3)))
; __device__ __forceinline__ void attn_phase(const Params& p, LAS unsigned char* lds) {
;     ...
; #pragma unroll
;         for (int j = 0; j < 4; ++j) {
; #pragma unroll
;             for (int o = 1; o < 16; o <<= 1) ls[j] += __shfl_xor(ls[j], o);
;         }
;         __syncthreads();
; #pragma unroll
;         for (int di = 0; di < 8; ++di) *(LAS u32x4*)(VtL + (db * 8 + di) * 264 + keyb * 8) = tr_col(vin, di);
;         __syncthreads();
;         f32x4 oa[8];
; #pragma unroll
;         for (int nb = 0; nb < 8; ++nb) oa[nb] = (f32x4){0.f, 0.f, 0.f, 0.f};
; #pragma unroll
;         for (int ks = 0; ks < 8; ++ks) {
;             const bf16x8 Pf = *(const LAS bf16x8*)(PLw + fr * 264 + ks * 32 + fq * 8);
; #pragma unroll
;             for (int nb = 0; nb < 8; ++nb) {
;                 const bf16x8 Vf = *(const LAS bf16x8*)(VtL + (nb * 16 + fr) * 264 + ks * 32 + fq * 8);
;                 oa[nb] = __builtin_amdgcn_mfma_f32_16x16x32_bf16(Pf, Vf, oa[nb], 0, 0, 0);
	v_add_f32_e32 v32, v35, v32
	s_nop 1
	v_mov_b32_dpp v35, v32 quad_perm:[2,3,0,1] row_mask:0xf bank_mask:0xf
	s_waitcnt lgkmcnt(0)
	v_add_f32_e32 v32, v32, v35
	s_nop 1
	v_mov_b32_dpp v35, v32 row_half_mirror row_mask:0xf bank_mask:0xf
	s_waitcnt lgkmcnt(0)
	v_add_f32_e32 v32, v32, v35
	s_nop 1
	v_mov_b32_dpp v35, v32 row_mirror row_mask:0xf bank_mask:0xf
	s_waitcnt lgkmcnt(0)
	v_add_f32_e32 v46, v32, v35
	s_nop 1
	v_mov_b32_dpp v32, v40 quad_perm:[1,0,3,2] row_mask:0xf bank_mask:0xf
	s_waitcnt lgkmcnt(0)
	v_add_f32_e32 v32, v40, v32
	s_nop 1
	v_mov_b32_dpp v35, v32 quad_perm:[2,3,0,1] row_mask:0xf bank_mask:0xf
	s_waitcnt lgkmcnt(0)
	v_add_f32_e32 v32, v32, v35
	s_nop 1
	v_mov_b32_dpp v35, v32 row_half_mirror row_mask:0xf bank_mask:0xf
	s_waitcnt lgkmcnt(0)
	v_add_f32_e32 v44, v32, v35
	s_nop 1
	v_mov_b32_dpp v32, v34 quad_perm:[1,0,3,2] row_mask:0xf bank_mask:0xf
	s_waitcnt vmcnt(0)
	v_and_b32_e32 v35, 0xffff, v28
	v_lshl_or_b32 v35, v24, 16, v35
	s_nop 1
	v_mov_b32_dpp v45, v44 row_mirror row_mask:0xf bank_mask:0xf
	s_waitcnt lgkmcnt(1)
	v_add_f32_e32 v32, v34, v32
	s_nop 1
	v_mov_b32_dpp v34, v32 quad_perm:[2,3,0,1] row_mask:0xf bank_mask:0xf
	s_waitcnt lgkmcnt(0)
	v_add_f32_e32 v32, v32, v34
	s_nop 1
	v_mov_b32_dpp v34, v32 row_half_mirror row_mask:0xf bank_mask:0xf
	s_waitcnt lgkmcnt(0)
	v_add_f32_e32 v42, v32, v34
	s_nop 1
	v_mov_b32_dpp v32, v33 quad_perm:[1,0,3,2] row_mask:0xf bank_mask:0xf
	v_and_b32_e32 v34, 0xffff, v20
	v_lshl_or_b32 v34, v16, 16, v34
	s_nop 1
	v_mov_b32_dpp v43, v42 row_mirror row_mask:0xf bank_mask:0xf
	s_waitcnt lgkmcnt(1)
	v_add_f32_e32 v32, v33, v32
	s_nop 1
	v_mov_b32_dpp v33, v32 quad_perm:[2,3,0,1] row_mask:0xf bank_mask:0xf
	s_waitcnt lgkmcnt(0)
	v_add_f32_e32 v32, v32, v33
	s_nop 1
	v_mov_b32_dpp v33, v32 row_half_mirror row_mask:0xf bank_mask:0xf
	s_waitcnt lgkmcnt(0)
	v_add_f32_e32 v40, v32, v33
	v_and_b32_e32 v32, 0xffff, v4
	v_and_b32_e32 v33, 0xffff, v12
	v_lshl_or_b32 v32, v0, 16, v32
	v_lshl_or_b32 v33, v8, 16, v33
	v_lshrrev_b32_e32 v4, 16, v4
	ds_write_b128 v140, v[32:35]
	v_and_or_b32 v32, v0, s85, v4
	v_lshrrev_b32_e32 v0, 16, v12
	v_and_or_b32 v33, v8, s85, v0
	v_lshrrev_b32_e32 v0, 16, v20
	v_and_or_b32 v34, v16, s85, v0
	v_lshrrev_b32_e32 v0, 16, v28
	v_and_or_b32 v35, v24, s85, v0
	v_and_b32_e32 v0, 0xffff, v5
	ds_write_b128 v140, v[32:35] offset:528
	v_lshl_or_b32 v32, v1, 16, v0
	v_and_b32_e32 v0, 0xffff, v13
	v_lshl_or_b32 v33, v9, 16, v0
	v_and_b32_e32 v0, 0xffff, v21
	v_lshl_or_b32 v34, v17, 16, v0
	v_and_b32_e32 v0, 0xffff, v29
	v_lshl_or_b32 v35, v25, 16, v0
	v_lshrrev_b32_e32 v0, 16, v5
	ds_write_b128 v140, v[32:35] offset:1056
	v_and_or_b32 v32, v1, s85, v0
	v_lshrrev_b32_e32 v0, 16, v13
	v_and_or_b32 v33, v9, s85, v0
	v_lshrrev_b32_e32 v0, 16, v21
	v_and_or_b32 v34, v17, s85, v0
	v_lshrrev_b32_e32 v0, 16, v29
	v_and_or_b32 v35, v25, s85, v0
	v_and_b32_e32 v0, 0xffff, v6
	ds_write_b128 v140, v[32:35] offset:1584
	v_lshl_or_b32 v32, v2, 16, v0
	v_and_b32_e32 v0, 0xffff, v14
	v_lshl_or_b32 v33, v10, 16, v0
	v_and_b32_e32 v0, 0xffff, v22
	v_lshl_or_b32 v34, v18, 16, v0
	v_and_b32_e32 v0, 0xffff, v30
	v_lshl_or_b32 v35, v26, 16, v0
	v_lshrrev_b32_e32 v0, 16, v6
	ds_write_b128 v140, v[32:35] offset:2112
	v_and_or_b32 v32, v2, s85, v0
	v_lshrrev_b32_e32 v0, 16, v14
	v_and_or_b32 v33, v10, s85, v0
	v_lshrrev_b32_e32 v0, 16, v22
	v_and_or_b32 v34, v18, s85, v0
	v_lshrrev_b32_e32 v0, 16, v30
	v_and_or_b32 v35, v26, s85, v0
	v_and_b32_e32 v0, 0xffff, v7
	ds_write_b128 v140, v[32:35] offset:2640
	v_lshl_or_b32 v32, v3, 16, v0
	v_and_b32_e32 v0, 0xffff, v15
	v_lshl_or_b32 v33, v11, 16, v0
	v_and_b32_e32 v0, 0xffff, v23
	v_lshl_or_b32 v34, v19, 16, v0
	v_and_b32_e32 v0, 0xffff, v31
	v_lshl_or_b32 v35, v27, 16, v0
	v_lshrrev_b32_e32 v0, 16, v7
	v_and_or_b32 v0, v3, s85, v0
	v_lshrrev_b32_e32 v1, 16, v15
	v_lshrrev_b32_e32 v2, 16, v23
	v_lshrrev_b32_e32 v3, 16, v31
	v_and_or_b32 v1, v11, s85, v1
	v_and_or_b32 v2, v19, s85, v2
	v_and_or_b32 v3, v27, s85, v3
	ds_write_b128 v140, v[32:35] offset:3168
	ds_write_b128 v140, v[0:3] offset:3696
	s_waitcnt lgkmcnt(0)
	s_barrier
	ds_read_b128 v[0:3], v117
	ds_read_b128 v[4:7], v47
	ds_read_b128 v[8:11], v141
	ds_read_b128 v[32:35], v141 offset:50688
	ds_read_b128 v[12:15], v141 offset:8448
	ds_read_b128 v[16:19], v141 offset:16896
	ds_read_b128 v[20:23], v141 offset:25344
	ds_read_b128 v[24:27], v141 offset:33792
	ds_read_b128 v[28:31], v141 offset:42240
	s_waitcnt lgkmcnt(7)
	v_mfma_f32_16x16x32_bf16 v[4:7], v[0:3], v[4:7], 0
	ds_bpermute_b32 v41, v129, v40
	s_waitcnt lgkmcnt(7)
	v_mfma_f32_16x16x32_bf16 v[8:11], v[0:3], v[8:11], 0
	s_waitcnt lgkmcnt(5)
	v_mfma_f32_16x16x32_bf16 v[12:15], v[0:3], v[12:15], 0
	s_waitcnt lgkmcnt(4)
	v_mfma_f32_16x16x32_bf16 v[16:19], v[0:3], v[16:19], 0
	s_waitcnt lgkmcnt(3)
	v_mfma_f32_16x16x32_bf16 v[20:23], v[0:3], v[20:23], 0
	s_waitcnt lgkmcnt(2)
	v_mfma_f32_16x16x32_bf16 v[24:27], v[0:3], v[24:27], 0
	s_waitcnt lgkmcnt(1)
	v_mfma_f32_16x16x32_bf16 v[28:31], v[0:3], v[28:31], 0
	v_mfma_f32_16x16x32_bf16 v[0:3], v[0:3], v[32:35], 0
	ds_read_b128 v[32:35], v117 offset:64
	ds_read_b128 v[48:51], v47 offset:64
	s_waitcnt lgkmcnt(0)
	v_mfma_f32_16x16x32_bf16 v[4:7], v[32:35], v[48:51], v[4:7]
	ds_read_b128 v[48:51], v141 offset:64
	s_waitcnt lgkmcnt(0)
	v_mfma_f32_16x16x32_bf16 v[8:11], v[32:35], v[48:51], v[8:11]
	ds_read_b128 v[48:51], v141 offset:8512
	s_waitcnt lgkmcnt(0)
	v_mfma_f32_16x16x32_bf16 v[12:15], v[32:35], v[48:51], v[12:15]
	ds_read_b128 v[48:51], v141 offset:16960
	s_waitcnt lgkmcnt(0)
	v_mfma_f32_16x16x32_bf16 v[16:19], v[32:35], v[48:51], v[16:19]
	ds_read_b128 v[48:51], v141 offset:25408
	s_waitcnt lgkmcnt(0)
; #define LAS __attribute__((address_space(3)))
; __device__ __forceinline__ void attn_phase(const Params& p, LAS unsigned char* lds) {
;     ...
; #pragma unroll
;         for (int ks = 0; ks < 8; ++ks) {
;             const bf16x8 Pf = *(const LAS bf16x8*)(PLw + fr * 264 + ks * 32 + fq * 8);
; #pragma unroll
;             for (int nb = 0; nb < 8; ++nb) {
;                 const bf16x8 Vf = *(const LAS bf16x8*)(VtL + (nb * 16 + fr) * 264 + ks * 32 + fq * 8);
;                 oa[nb] = __builtin_amdgcn_mfma_f32_16x16x32_bf16(Pf, Vf, oa[nb], 0, 0, 0);
;             }
;         }
	v_mfma_f32_16x16x32_bf16 v[20:23], v[32:35], v[48:51], v[20:23]
	ds_read_b128 v[48:51], v141 offset:33856
	s_waitcnt lgkmcnt(0)
	v_mfma_f32_16x16x32_bf16 v[24:27], v[32:35], v[48:51], v[24:27]
	ds_read_b128 v[48:51], v141 offset:42304
	s_waitcnt lgkmcnt(0)
	v_mfma_f32_16x16x32_bf16 v[28:31], v[32:35], v[48:51], v[28:31]
	ds_read_b128 v[48:51], v141 offset:50752
	s_waitcnt lgkmcnt(0)
	v_mfma_f32_16x16x32_bf16 v[0:3], v[32:35], v[48:51], v[0:3]
	ds_read_b128 v[32:35], v117 offset:128
	ds_read_b128 v[48:51], v47 offset:128
	s_waitcnt lgkmcnt(0)
	v_mfma_f32_16x16x32_bf16 v[4:7], v[32:35], v[48:51], v[4:7]
	ds_read_b128 v[48:51], v141 offset:128
	s_waitcnt lgkmcnt(0)
	v_mfma_f32_16x16x32_bf16 v[8:11], v[32:35], v[48:51], v[8:11]
	ds_read_b128 v[48:51], v141 offset:8576
	s_waitcnt lgkmcnt(0)
	v_mfma_f32_16x16x32_bf16 v[12:15], v[32:35], v[48:51], v[12:15]
	ds_read_b128 v[48:51], v141 offset:17024
	s_waitcnt lgkmcnt(0)
	v_mfma_f32_16x16x32_bf16 v[16:19], v[32:35], v[48:51], v[16:19]
	ds_read_b128 v[48:51], v141 offset:25472
	s_waitcnt lgkmcnt(0)
	v_mfma_f32_16x16x32_bf16 v[20:23], v[32:35], v[48:51], v[20:23]
	ds_read_b128 v[48:51], v141 offset:33920
	s_waitcnt lgkmcnt(0)
	v_mfma_f32_16x16x32_bf16 v[24:27], v[32:35], v[48:51], v[24:27]
	ds_read_b128 v[48:51], v141 offset:42368
	s_waitcnt lgkmcnt(0)
	v_mfma_f32_16x16x32_bf16 v[28:31], v[32:35], v[48:51], v[28:31]
	ds_read_b128 v[48:51], v141 offset:50816
	s_waitcnt lgkmcnt(0)
	v_mfma_f32_16x16x32_bf16 v[0:3], v[32:35], v[48:51], v[0:3]
	ds_read_b128 v[32:35], v117 offset:192
	ds_read_b128 v[48:51], v47 offset:192
	s_waitcnt lgkmcnt(0)
	v_mfma_f32_16x16x32_bf16 v[4:7], v[32:35], v[48:51], v[4:7]
	ds_read_b128 v[48:51], v141 offset:192
	s_waitcnt lgkmcnt(0)
	v_mfma_f32_16x16x32_bf16 v[8:11], v[32:35], v[48:51], v[8:11]
	ds_read_b128 v[48:51], v141 offset:8640
	s_waitcnt lgkmcnt(0)
	v_mfma_f32_16x16x32_bf16 v[12:15], v[32:35], v[48:51], v[12:15]
	ds_read_b128 v[48:51], v141 offset:17088
	s_waitcnt lgkmcnt(0)
	v_mfma_f32_16x16x32_bf16 v[16:19], v[32:35], v[48:51], v[16:19]
	ds_read_b128 v[48:51], v141 offset:25536
	s_waitcnt lgkmcnt(0)
	v_mfma_f32_16x16x32_bf16 v[20:23], v[32:35], v[48:51], v[20:23]
	ds_read_b128 v[48:51], v141 offset:33984
	s_waitcnt lgkmcnt(0)
	v_mfma_f32_16x16x32_bf16 v[24:27], v[32:35], v[48:51], v[24:27]
	ds_read_b128 v[48:51], v141 offset:42432
	s_waitcnt lgkmcnt(0)
	v_mfma_f32_16x16x32_bf16 v[28:31], v[32:35], v[48:51], v[28:31]
	ds_read_b128 v[48:51], v141 offset:50880
	s_waitcnt lgkmcnt(0)
	v_mfma_f32_16x16x32_bf16 v[0:3], v[32:35], v[48:51], v[0:3]
	ds_read_b128 v[32:35], v117 offset:256
	ds_read_b128 v[48:51], v47 offset:256
	s_waitcnt lgkmcnt(0)
	v_mfma_f32_16x16x32_bf16 v[4:7], v[32:35], v[48:51], v[4:7]
	ds_read_b128 v[48:51], v141 offset:256
	s_waitcnt lgkmcnt(0)
	v_mfma_f32_16x16x32_bf16 v[8:11], v[32:35], v[48:51], v[8:11]
	ds_read_b128 v[48:51], v141 offset:8704
	s_waitcnt lgkmcnt(0)
	v_mfma_f32_16x16x32_bf16 v[12:15], v[32:35], v[48:51], v[12:15]
	ds_read_b128 v[48:51], v141 offset:17152
	s_waitcnt lgkmcnt(0)
	v_mfma_f32_16x16x32_bf16 v[16:19], v[32:35], v[48:51], v[16:19]
	ds_read_b128 v[48:51], v141 offset:25600
	s_waitcnt lgkmcnt(0)
	v_mfma_f32_16x16x32_bf16 v[20:23], v[32:35], v[48:51], v[20:23]
	ds_read_b128 v[48:51], v141 offset:34048
	s_waitcnt lgkmcnt(0)
	v_mfma_f32_16x16x32_bf16 v[24:27], v[32:35], v[48:51], v[24:27]
	ds_read_b128 v[48:51], v141 offset:42496
	s_waitcnt lgkmcnt(0)
	v_mfma_f32_16x16x32_bf16 v[28:31], v[32:35], v[48:51], v[28:31]
	ds_read_b128 v[48:51], v141 offset:50944
	s_waitcnt lgkmcnt(0)
	v_mfma_f32_16x16x32_bf16 v[0:3], v[32:35], v[48:51], v[0:3]
	ds_read_b128 v[32:35], v117 offset:320
	ds_read_b128 v[48:51], v47 offset:320
	s_waitcnt lgkmcnt(0)
	v_mfma_f32_16x16x32_bf16 v[4:7], v[32:35], v[48:51], v[4:7]
	ds_read_b128 v[48:51], v141 offset:320
	s_waitcnt lgkmcnt(0)
	v_mfma_f32_16x16x32_bf16 v[8:11], v[32:35], v[48:51], v[8:11]
	ds_read_b128 v[48:51], v141 offset:8768
	s_waitcnt lgkmcnt(0)
	v_mfma_f32_16x16x32_bf16 v[12:15], v[32:35], v[48:51], v[12:15]
	ds_read_b128 v[48:51], v141 offset:17216
	s_waitcnt lgkmcnt(0)
	v_mfma_f32_16x16x32_bf16 v[16:19], v[32:35], v[48:51], v[16:19]
	ds_read_b128 v[48:51], v141 offset:25664
	s_waitcnt lgkmcnt(0)
	v_mfma_f32_16x16x32_bf16 v[20:23], v[32:35], v[48:51], v[20:23]
	ds_read_b128 v[48:51], v141 offset:34112
	s_waitcnt lgkmcnt(0)
	v_mfma_f32_16x16x32_bf16 v[24:27], v[32:35], v[48:51], v[24:27]
	ds_read_b128 v[48:51], v141 offset:42560
	s_waitcnt lgkmcnt(0)
; #define LAS __attribute__((address_space(3)))
; __device__ __forceinline__ bf16_t f2bf(float f) { return (bf16_t)(cvt_pk_bf16(f, 0.f) & 0xffffu); }
; __device__ __forceinline__ void attn_phase(const Params& p, LAS unsigned char* lds) {
;     ...
; #pragma unroll
;         for (int ks = 0; ks < 8; ++ks) {
;             const bf16x8 Pf = *(const LAS bf16x8*)(PLw + fr * 264 + ks * 32 + fq * 8);
; #pragma unroll
;             for (int nb = 0; nb < 8; ++nb) {
;                 const bf16x8 Vf = *(const LAS bf16x8*)(VtL + (nb * 16 + fr) * 264 + ks * 32 + fq * 8);
;                 oa[nb] = __builtin_amdgcn_mfma_f32_16x16x32_bf16(Pf, Vf, oa[nb], 0, 0, 0);
;             }
;         }
; #pragma unroll
;         for (int j = 0; j < 4; ++j) {
;             const size_t tok = (size_t)(r + d * (i0 + wid * 16 + fq * 4 + j));
;             const float inv = 1.0f / ls[j];
;             bf16_t* orow = og + ((size_t)g * SEQ + tok) * 1024 + h * 128 + fr;
; #pragma unroll
;             for (int nb = 0; nb < 8; ++nb) orow[nb * 16] = f2bf(oa[nb][j] * inv);
;             if (fr == 0) lse[((size_t)g * SEQ + tok) * 8 + h] = mx[j] + logf(ls[j]);
;         }
	v_mfma_f32_16x16x32_bf16 v[28:31], v[32:35], v[48:51], v[28:31]
	ds_read_b128 v[48:51], v141 offset:51008
	s_waitcnt lgkmcnt(0)
	v_mfma_f32_16x16x32_bf16 v[0:3], v[32:35], v[48:51], v[0:3]
	ds_read_b128 v[32:35], v117 offset:384
	ds_read_b128 v[48:51], v47 offset:384
	s_waitcnt lgkmcnt(0)
	v_mfma_f32_16x16x32_bf16 v[4:7], v[32:35], v[48:51], v[4:7]
	ds_read_b128 v[48:51], v141 offset:384
	s_waitcnt lgkmcnt(0)
	v_mfma_f32_16x16x32_bf16 v[8:11], v[32:35], v[48:51], v[8:11]
	ds_read_b128 v[48:51], v141 offset:8832
	s_waitcnt lgkmcnt(0)
	v_mfma_f32_16x16x32_bf16 v[12:15], v[32:35], v[48:51], v[12:15]
	ds_read_b128 v[48:51], v141 offset:17280
	s_waitcnt lgkmcnt(0)
	v_mfma_f32_16x16x32_bf16 v[16:19], v[32:35], v[48:51], v[16:19]
	ds_read_b128 v[48:51], v141 offset:25728
	s_waitcnt lgkmcnt(0)
	v_mfma_f32_16x16x32_bf16 v[48:51], v[32:35], v[48:51], v[20:23]
	s_nop 2
	ds_read_b128 v[20:23], v141 offset:34176
	s_waitcnt lgkmcnt(0)
	v_mfma_f32_16x16x32_bf16 v[52:55], v[32:35], v[20:23], v[24:27]
	ds_read_b128 v[20:23], v141 offset:42624
	s_waitcnt lgkmcnt(0)
	v_mfma_f32_16x16x32_bf16 v[56:59], v[32:35], v[20:23], v[28:31]
	ds_read_b128 v[20:23], v141 offset:51072
	s_waitcnt lgkmcnt(0)
	v_mfma_f32_16x16x32_bf16 v[0:3], v[32:35], v[20:23], v[0:3]
	ds_read_b128 v[32:35], v117 offset:448
	ds_read_b128 v[20:23], v47 offset:448
	v_or_b32_e32 v47, v142, v115
	s_waitcnt lgkmcnt(0)
	v_mfma_f32_16x16x32_bf16 v[28:31], v[32:35], v[20:23], v[4:7]
	s_nop 2
	ds_read_b128 v[4:7], v141 offset:448
	s_waitcnt lgkmcnt(0)
	v_mfma_f32_16x16x32_bf16 v[24:27], v[32:35], v[4:7], v[8:11]
	ds_read_b128 v[4:7], v141 offset:8896
	s_waitcnt lgkmcnt(0)
	v_mfma_f32_16x16x32_bf16 v[20:23], v[32:35], v[4:7], v[12:15]
	ds_read_b128 v[4:7], v141 offset:17344
	s_waitcnt lgkmcnt(0)
	v_mfma_f32_16x16x32_bf16 v[16:19], v[32:35], v[4:7], v[16:19]
	ds_read_b128 v[4:7], v141 offset:25792
	s_waitcnt lgkmcnt(0)
	v_mfma_f32_16x16x32_bf16 v[12:15], v[32:35], v[4:7], v[48:51]
	ds_read_b128 v[4:7], v141 offset:34240
	s_nop 1
	ds_read_b128 v[48:51], v141 offset:51136
	s_waitcnt lgkmcnt(0)
	v_mfma_f32_16x16x32_bf16 v[0:3], v[32:35], v[48:51], v[0:3]
	v_div_scale_f32 v48, s[78:79], v46, v46, 1.0
	v_rcp_f32_e32 v49, v48
	v_mfma_f32_16x16x32_bf16 v[8:11], v[32:35], v[4:7], v[52:55]
	ds_read_b128 v[4:7], v141 offset:42688
	v_fma_f32 v50, -v48, v49, 1.0
	v_fmac_f32_e32 v49, v50, v49
	v_div_scale_f32 v50, vcc, 1.0, v46, 1.0
	v_mul_f32_e32 v51, v50, v49
	s_waitcnt lgkmcnt(0)
	v_mfma_f32_16x16x32_bf16 v[4:7], v[32:35], v[4:7], v[56:59]
	v_lshlrev_b32_e32 v34, s47, v47
	v_fma_f32 v52, -v48, v51, v50
	v_add_u32_e32 v34, s50, v34
	v_fmac_f32_e32 v51, v52, v49
	v_ashrrev_i32_e32 v35, 31, v34
	v_fma_f32 v48, -v48, v51, v50
	v_lshl_add_u64 v[32:33], v[110:111], 0, s[2:3]
	s_lshl_b32 s2, s51, 2
	v_div_fmas_f32 v48, v48, v49, v51
	v_lshl_add_u64 v[34:35], s[76:77], 0, v[34:35]
	s_add_u32 s40, s95, s2
	v_readlane_b32 s2, v239, 42
	v_div_fixup_f32 v50, v48, v46, 1.0
	v_lshlrev_b64 v[48:49], 11, v[34:35]
	s_addc_u32 s41, s2, 0
	v_lshl_add_u64 v[48:49], v[32:33], 0, v[48:49]
	v_mul_f32_e32 v28, v50, v28
	v_mul_f32_e32 v24, v50, v24
	v_mul_f32_e32 v20, v50, v20
	v_mul_f32_e32 v16, v50, v16
	v_mul_f32_e32 v12, v50, v12
	v_mul_f32_e32 v8, v50, v8
	v_mul_f32_e32 v4, v50, v4
	v_mul_f32_e32 v0, v50, v0
	v_cvt_pk_bf16_f32 v28, v28, v169
	global_store_short v[48:49], v28, off
	v_cvt_pk_bf16_f32 v24, v24, v169
	global_store_short v[48:49], v24, off offset:32
	v_cvt_pk_bf16_f32 v20, v20, v169
	global_store_short v[48:49], v20, off offset:64
	v_cvt_pk_bf16_f32 v16, v16, v169
	global_store_short v[48:49], v16, off offset:96
	v_cvt_pk_bf16_f32 v12, v12, v169
	global_store_short v[48:49], v12, off offset:128
	v_cvt_pk_bf16_f32 v8, v8, v169
	global_store_short v[48:49], v8, off offset:160
	v_cvt_pk_bf16_f32 v4, v4, v169
	global_store_short v[48:49], v4, off offset:192
	v_cvt_pk_bf16_f32 v0, v0, v169
	global_store_short v[48:49], v0, off offset:224
	s_and_saveexec_b64 s[78:79], s[4:5]
	s_cbranch_execz .LBB0_212
	s_mov_b32 s2, 0x800000
	v_cmp_gt_f32_e32 vcc, s2, v46
	s_mov_b32 s2, 0x3f317217
	v_lshlrev_b64 v[34:35], 5, v[34:35]
	v_cndmask_b32_e64 v0, 0, 32, vcc
	v_ldexp_f32 v0, v46, v0
	v_log_f32_e32 v0, v0
	v_cndmask_b32_e32 v4, 0, v205, vcc
	v_lshl_add_u64 v[34:35], s[40:41], 0, v[34:35]
	v_mul_f32_e32 v8, 0x3f317217, v0
	v_fma_f32 v8, v0, s2, -v8
	v_fmac_f32_e32 v8, 0x3377d1cf, v0
	s_mov_b32 s2, 0x7f800000
	v_fmac_f32_e32 v8, 0x3f317217, v0
	v_cmp_lt_f32_e64 vcc, |v0|, s2
	s_nop 1
	v_cndmask_b32_e32 v0, v0, v8, vcc
	v_sub_f32_e32 v0, v0, v4
	v_add_f32_e32 v0, v39, v0
	global_store_dword v[34:35], v0, off
